# mix phase: attention item epilogues (8 gain loads issued together) and spatial unit epilogue (24 loads together) de-serialised
# speedup vs baseline: 1.0210x; 1.0070x over previous
.LBB0_114:
	v_sub_f32_e32 v92, v92, v163
	v_sub_f32_e32 v93, v93, v163
	v_exp_f32_e32 v92, v92
	v_exp_f32_e32 v93, v93
	v_sub_f32_e32 v88, v88, v163
	v_sub_f32_e32 v94, v94, v163
	v_exp_f32_e32 v105, v88
	v_sub_f32_e32 v88, v89, v163
	v_exp_f32_e32 v94, v94
	v_sub_f32_e32 v95, v95, v163
	v_exp_f32_e32 v106, v88
	v_sub_f32_e32 v88, v90, v163
	v_exp_f32_e32 v95, v95
	v_exp_f32_e32 v107, v88
	v_sub_f32_e32 v88, v91, v163
	v_exp_f32_e32 v108, v88
	v_cvt_pk_bf16_f32 v88, v92, v93
	v_add_f32_e32 v92, 0, v92
	v_add_f32_e32 v92, v93, v92
	v_add_f32_e32 v92, v94, v92
	v_sub_f32_e32 v72, v100, v163
	v_add_f32_e32 v92, v95, v92
	v_exp_f32_e32 v100, v72
	v_sub_f32_e32 v72, v101, v163
	v_add_f32_e32 v92, v105, v92
	v_exp_f32_e32 v101, v72
	v_sub_f32_e32 v72, v102, v163
	v_add_f32_e32 v92, v106, v92
	v_exp_f32_e32 v102, v72
	v_sub_f32_e32 v72, v103, v163
	v_add_f32_e32 v92, v107, v92
	v_exp_f32_e32 v103, v72
	v_sub_f32_e32 v72, v96, v163
	v_add_f32_e32 v92, v108, v92
	v_exp_f32_e32 v96, v72
	v_sub_f32_e32 v72, v97, v163
	v_add_f32_e32 v92, v100, v92
	v_exp_f32_e32 v97, v72
	v_sub_f32_e32 v72, v98, v163
	v_add_f32_e32 v92, v101, v92
	v_exp_f32_e32 v98, v72
	v_sub_f32_e32 v72, v99, v163
	v_add_f32_e32 v92, v102, v92
	s_waitcnt lgkmcnt(0)
	v_add_f32_e32 v3, v3, v104
	v_add_f32_e32 v0, v0, v2
	v_exp_f32_e32 v99, v72
	v_add_f32_e32 v92, v103, v92
	v_mul_f32_e32 v3, 0x3fb8aa3b, v3
	v_mul_f32_e32 v0, 0x3fb8aa3b, v0
	v_add_f32_e32 v92, v96, v92
	v_exp_f32_e32 v3, v3
	v_exp_f32_e32 v0, v0
	v_add_f32_e32 v92, v97, v92
	v_add_f32_e32 v2, v98, v92
	v_add_f32_e32 v2, v99, v2
	v_cvt_pk_bf16_f32 v91, v107, v108
	v_add_f32_e32 v108, v141, v2
	v_sub_f32_e32 v2, v3, v0
	v_sub_f32_e32 v0, v84, v161
	v_exp_f32_e32 v0, v0
	v_sub_f32_e32 v3, v85, v161
	v_exp_f32_e32 v3, v3
	v_sub_f32_e32 v84, v86, v161
	v_exp_f32_e32 v84, v84
	v_sub_f32_e32 v85, v87, v161
	v_exp_f32_e32 v85, v85
	v_sub_f32_e32 v80, v80, v161
	v_add_f32_e32 v86, 0, v0
	v_exp_f32_e32 v80, v80
	v_sub_f32_e32 v81, v81, v161
	v_add_f32_e32 v86, v3, v86
	v_exp_f32_e32 v81, v81
	v_sub_f32_e32 v82, v82, v161
	v_add_f32_e32 v86, v84, v86
	v_exp_f32_e32 v82, v82
	v_sub_f32_e32 v83, v83, v161
	v_add_f32_e32 v86, v85, v86
	v_exp_f32_e32 v83, v83
	v_sub_f32_e32 v76, v76, v161
	v_add_f32_e32 v86, v80, v86
	v_exp_f32_e32 v76, v76
	v_sub_f32_e32 v77, v77, v161
	v_add_f32_e32 v86, v81, v86
	v_exp_f32_e32 v77, v77
	v_sub_f32_e32 v78, v78, v161
	v_add_f32_e32 v86, v82, v86
	v_exp_f32_e32 v78, v78
	v_sub_f32_e32 v79, v79, v161
	v_add_f32_e32 v86, v83, v86
	v_exp_f32_e32 v79, v79
	v_sub_f32_e32 v68, v68, v161
	v_add_f32_e32 v86, v76, v86
	v_exp_f32_e32 v87, v68
	v_sub_f32_e32 v68, v69, v161
	v_add_f32_e32 v86, v77, v86
	v_exp_f32_e32 v92, v68
	v_sub_f32_e32 v68, v70, v161
	v_add_f32_e32 v86, v78, v86
	v_exp_f32_e32 v93, v68
	v_sub_f32_e32 v68, v71, v161
	v_cvt_pk_bf16_f32 v89, v94, v95
	v_add_f32_e32 v86, v79, v86
	v_exp_f32_e32 v94, v68
	v_add_f32_e32 v68, v87, v86
	v_add_f32_e32 v68, v92, v68
	v_add_f32_e32 v68, v93, v68
	v_add_f32_e32 v68, v94, v68
	v_add_f32_e32 v109, v140, v68
	v_cvt_pk_bf16_f32 v68, v0, v3
	v_cvt_pk_bf16_f32 v70, v80, v81
	v_add_u32_e32 v0, 0x8000, v117
	ds_read_b64 v[80:81], v0 offset:0
	v_cvt_pk_bf16_f32 v71, v82, v83
	v_add_u32_e32 v3, 0x8000, v137
	ds_read_b64 v[82:83], v3 offset:0
	v_cvt_pk_bf16_f32 v69, v84, v85
	v_add_u32_e32 v110, 0x8000, v138
	ds_read_b64 v[84:85], v110 offset:0
	v_cvt_pk_bf16_f32 v76, v76, v77
	v_cvt_pk_bf16_f32 v77, v78, v79
	v_cvt_pk_bf16_f32 v78, v87, v92
	v_add_u32_e32 v111, 0x8000, v139
	ds_read_b64 v[86:87], v111 offset:0
	v_cvt_pk_bf16_f32 v79, v93, v94
	ds_read_b64 v[92:93], v0 offset:2048
	ds_read_b64 v[94:95], v3 offset:2048
	v_cvt_pk_bf16_f32 v74, v96, v97
	ds_read_b64 v[96:97], v110 offset:2048
	v_cvt_pk_bf16_f32 v75, v98, v99
	ds_read_b64 v[98:99], v111 offset:2048
	v_cvt_pk_bf16_f32 v72, v100, v101
	ds_read_b64 v[100:101], v0 offset:4096
	v_cvt_pk_bf16_f32 v73, v102, v103
	ds_read_b64 v[102:103], v3 offset:4096
	v_cvt_pk_bf16_f32 v90, v105, v106
	ds_read_b64 v[104:105], v110 offset:4096
	ds_read_b64 v[106:107], v111 offset:4096
	s_waitcnt lgkmcnt(8)
	s_nop 1
	v_mfma_f32_16x16x32_bf16 v[64:67], v[80:83], v[88:91], v[64:67]
	v_mfma_f32_16x16x32_bf16 v[80:83], v[80:83], v[68:71], v[60:63]
	v_mfma_f32_16x16x32_bf16 v[60:63], v[84:87], v[72:75], v[64:67]
	v_mfma_f32_16x16x32_bf16 v[64:67], v[84:87], v[76:79], v[80:83]
	ds_read_b64 v[80:81], v0 offset:6144
	ds_read_b64 v[82:83], v3 offset:6144
	ds_read_b64 v[84:85], v110 offset:6144
	ds_read_b64 v[86:87], v111 offset:6144
	s_waitcnt lgkmcnt(8)
	v_mfma_f32_16x16x32_bf16 v[56:59], v[92:95], v[88:91], v[56:59]
	v_mfma_f32_16x16x32_bf16 v[92:95], v[92:95], v[68:71], v[52:55]
	v_mfma_f32_16x16x32_bf16 v[52:55], v[96:99], v[72:75], v[56:59]
	v_mfma_f32_16x16x32_bf16 v[56:59], v[96:99], v[76:79], v[92:95]
	ds_read_b64 v[92:93], v0 offset:8192
	ds_read_b64 v[94:95], v3 offset:8192
	ds_read_b64 v[96:97], v110 offset:8192
	ds_read_b64 v[98:99], v111 offset:8192
	s_waitcnt lgkmcnt(8)
	v_mfma_f32_16x16x32_bf16 v[48:51], v[100:103], v[88:91], v[48:51]
	v_mfma_f32_16x16x32_bf16 v[100:103], v[100:103], v[68:71], v[44:47]
	v_mfma_f32_16x16x32_bf16 v[44:47], v[104:107], v[72:75], v[48:51]
	v_mfma_f32_16x16x32_bf16 v[48:51], v[104:107], v[76:79], v[100:103]
	ds_read_b64 v[100:101], v0 offset:10240
	ds_read_b64 v[102:103], v3 offset:10240
	ds_read_b64 v[104:105], v110 offset:10240
	ds_read_b64 v[106:107], v111 offset:10240
	s_waitcnt lgkmcnt(8)
	v_mfma_f32_16x16x32_bf16 v[40:43], v[80:83], v[88:91], v[40:43]
	v_mfma_f32_16x16x32_bf16 v[80:83], v[80:83], v[68:71], v[36:39]
	v_mfma_f32_16x16x32_bf16 v[36:39], v[84:87], v[72:75], v[40:43]
	v_mfma_f32_16x16x32_bf16 v[40:43], v[84:87], v[76:79], v[80:83]
	ds_read_b64 v[80:81], v0 offset:12288
	ds_read_b64 v[82:83], v3 offset:12288
	ds_read_b64 v[84:85], v110 offset:12288
	ds_read_b64 v[86:87], v111 offset:12288
	s_waitcnt lgkmcnt(8)
	v_mfma_f32_16x16x32_bf16 v[32:35], v[92:95], v[88:91], v[32:35]
	v_mfma_f32_16x16x32_bf16 v[92:95], v[92:95], v[68:71], v[28:31]
	v_mfma_f32_16x16x32_bf16 v[28:31], v[96:99], v[72:75], v[32:35]
	v_mfma_f32_16x16x32_bf16 v[32:35], v[96:99], v[76:79], v[92:95]
	ds_read_b64 v[92:93], v0 offset:14336
	ds_read_b64 v[94:95], v3 offset:14336
	ds_read_b64 v[96:97], v110 offset:14336
	ds_read_b64 v[98:99], v111 offset:14336
	s_waitcnt lgkmcnt(8)
	v_mfma_f32_16x16x32_bf16 v[24:27], v[100:103], v[88:91], v[24:27]
	v_mfma_f32_16x16x32_bf16 v[100:103], v[100:103], v[68:71], v[16:19]
	v_mfma_f32_16x16x32_bf16 v[16:19], v[104:107], v[72:75], v[24:27]
	v_mfma_f32_16x16x32_bf16 v[100:103], v[104:107], v[76:79], v[100:103]
	s_waitcnt lgkmcnt(4)
	v_mfma_f32_16x16x32_bf16 v[20:23], v[80:83], v[88:91], v[20:23]
	v_mfma_f32_16x16x32_bf16 v[24:27], v[80:83], v[68:71], v[8:11]
	v_mfma_f32_16x16x32_bf16 v[8:11], v[84:87], v[72:75], v[20:23]
	v_mfma_f32_16x16x32_bf16 v[80:83], v[84:87], v[76:79], v[24:27]
	s_waitcnt lgkmcnt(0)
	v_mfma_f32_16x16x32_bf16 v[12:15], v[92:95], v[88:91], v[12:15]
	v_mfma_f32_16x16x32_bf16 v[4:7], v[92:95], v[68:71], v[4:7]
	v_mfma_f32_16x16x32_bf16 v[68:71], v[96:99], v[72:75], v[12:15]
	v_mfma_f32_16x16x32_bf16 v[72:75], v[96:99], v[76:79], v[4:7]
	ds_bpermute_b32 v0, v136, v108
	s_waitcnt lgkmcnt(0)
	v_add_f32_e32 v0, v108, v0
	ds_bpermute_b32 v3, v135, v0
	s_waitcnt lgkmcnt(0)
	v_add_f32_e32 v0, v0, v3
	ds_bpermute_b32 v3, v136, v109
	v_div_scale_f32 v4, s[6:7], v0, v0, 1.0
	v_rcp_f32_e32 v5, v4
	s_waitcnt lgkmcnt(0)
	v_add_f32_e32 v3, v109, v3
	ds_bpermute_b32 v117, v135, v3
	v_fma_f32 v6, -v4, v5, 1.0
	v_fmac_f32_e32 v5, v6, v5
	v_div_scale_f32 v6, vcc, 1.0, v0, 1.0
	v_mul_f32_e32 v7, v6, v5
	v_fma_f32 v12, -v4, v7, v6
	v_fmac_f32_e32 v7, v12, v5
	v_fma_f32 v4, -v4, v7, v6
	s_waitcnt lgkmcnt(0)
	v_pk_add_f32 v[2:3], v[116:117], v[2:3]
	v_div_fmas_f32 v4, v4, v5, v7
	v_div_fixup_f32 v0, v4, v0, 1.0
	v_div_scale_f32 v4, s[6:7], v3, v3, v2
	v_rcp_f32_e32 v5, v4
	v_readlane_b32 s6, v217, 30
	v_readlane_b32 s7, v217, 31
	v_fma_f32 v6, -v4, v5, 1.0
	v_fmac_f32_e32 v5, v6, v5
	v_div_scale_f32 v6, vcc, v2, v3, v2
	v_mul_f32_e32 v7, v6, v5
	v_fma_f32 v12, -v4, v7, v6
	v_fmac_f32_e32 v7, v12, v5
	v_fma_f32 v4, -v4, v7, v6
	v_div_fmas_f32 v4, v4, v5, v7
	v_div_fixup_f32 v2, v4, v3, v2
	v_pk_mul_f32 v[4:5], v[64:65], v[2:3] op_sel_hi:[1,0]
	v_pk_mul_f32 v[6:7], v[66:67], v[2:3] op_sel_hi:[1,0]
	v_pk_fma_f32 v[12:13], v[60:61], v[0:1], v[4:5] op_sel_hi:[1,0,1] neg_lo:[0,0,1] neg_hi:[0,0,1]
	v_pk_fma_f32 v[6:7], v[62:63], v[0:1], v[6:7] op_sel_hi:[1,0,1] neg_lo:[0,0,1] neg_hi:[0,0,1]
	v_mul_f32_e32 v3, v13, v13
	v_fmac_f32_e32 v3, v12, v12
	v_fmac_f32_e32 v3, v6, v6
	v_fmac_f32_e32 v3, v7, v7
	v_pk_mul_f32 v[4:5], v[56:57], v[2:3] op_sel_hi:[1,0]
	v_pk_mul_f32 v[14:15], v[58:59], v[2:3] op_sel_hi:[1,0]
	v_pk_fma_f32 v[22:23], v[52:53], v[0:1], v[4:5] op_sel_hi:[1,0,1] neg_lo:[0,0,1] neg_hi:[0,0,1]
	v_pk_fma_f32 v[14:15], v[54:55], v[0:1], v[14:15] op_sel_hi:[1,0,1] neg_lo:[0,0,1] neg_hi:[0,0,1]
	v_mul_f32_e32 v4, v23, v23
	v_fmac_f32_e32 v4, v22, v22
	v_fmac_f32_e32 v4, v14, v14
	v_fmac_f32_e32 v4, v15, v15
	v_add_f32_e32 v3, v3, v4
	v_pk_mul_f32 v[4:5], v[48:49], v[2:3] op_sel_hi:[1,0]
	v_pk_mul_f32 v[20:21], v[50:51], v[2:3] op_sel_hi:[1,0]
	v_pk_fma_f32 v[44:45], v[44:45], v[0:1], v[4:5] op_sel_hi:[1,0,1] neg_lo:[0,0,1] neg_hi:[0,0,1]
	v_pk_mul_f32 v[4:5], v[40:41], v[2:3] op_sel_hi:[1,0]
	v_pk_fma_f32 v[26:27], v[46:47], v[0:1], v[20:21] op_sel_hi:[1,0,1] neg_lo:[0,0,1] neg_hi:[0,0,1]
	v_pk_fma_f32 v[24:25], v[36:37], v[0:1], v[4:5] op_sel_hi:[1,0,1] neg_lo:[0,0,1] neg_hi:[0,0,1]
	v_pk_mul_f32 v[20:21], v[42:43], v[2:3] op_sel_hi:[1,0]
	v_mov_b32_e32 v36, v25
	v_mov_b32_e32 v37, v45
	v_pk_fma_f32 v[20:21], v[38:39], v[0:1], v[20:21] op_sel_hi:[1,0,1] neg_lo:[0,0,1] neg_hi:[0,0,1]
	v_mov_b32_e32 v4, v24
	v_mov_b32_e32 v5, v44
	v_pk_mul_f32 v[36:37], v[36:37], v[36:37]
	s_nop 0
	v_pk_fma_f32 v[4:5], v[4:5], v[4:5], v[36:37]
	v_mov_b32_e32 v36, v20
	v_mov_b32_e32 v37, v26
	v_pk_fma_f32 v[4:5], v[36:37], v[36:37], v[4:5]
	v_mov_b32_e32 v36, v21
	v_mov_b32_e32 v37, v27
	v_pk_fma_f32 v[4:5], v[36:37], v[36:37], v[4:5]
	v_lshlrev_b32_e32 v37, 4, v134
	v_add_f32_e32 v3, v5, v3
	v_add_f32_e32 v3, v4, v3
	v_pk_mul_f32 v[4:5], v[32:33], v[2:3] op_sel_hi:[1,0]
	v_pk_mul_f32 v[32:33], v[34:35], v[2:3] op_sel_hi:[1,0]
	v_pk_fma_f32 v[34:35], v[28:29], v[0:1], v[4:5] op_sel_hi:[1,0,1] neg_lo:[0,0,1] neg_hi:[0,0,1]
	v_pk_mul_f32 v[4:5], v[100:101], v[2:3] op_sel_hi:[1,0]
	v_pk_mul_f32 v[28:29], v[102:103], v[2:3] op_sel_hi:[1,0]
	v_pk_fma_f32 v[16:17], v[16:17], v[0:1], v[4:5] op_sel_hi:[1,0,1] neg_lo:[0,0,1] neg_hi:[0,0,1]
	v_pk_fma_f32 v[18:19], v[18:19], v[0:1], v[28:29] op_sel_hi:[1,0,1] neg_lo:[0,0,1] neg_hi:[0,0,1]
	v_mov_b32_e32 v28, v17
	v_mov_b32_e32 v29, v35
	v_pk_fma_f32 v[30:31], v[30:31], v[0:1], v[32:33] op_sel_hi:[1,0,1] neg_lo:[0,0,1] neg_hi:[0,0,1]
	v_mov_b32_e32 v4, v16
	v_mov_b32_e32 v5, v34
	v_pk_mul_f32 v[28:29], v[28:29], v[28:29]
	s_nop 0
	v_pk_fma_f32 v[4:5], v[4:5], v[4:5], v[28:29]
	v_mov_b32_e32 v28, v18
	v_mov_b32_e32 v29, v30
	v_pk_fma_f32 v[4:5], v[28:29], v[28:29], v[4:5]
	v_mov_b32_e32 v28, v19
	v_mov_b32_e32 v29, v31
	v_pk_fma_f32 v[4:5], v[28:29], v[28:29], v[4:5]
	s_nop 0
	v_add_f32_e32 v3, v5, v3
	v_add_f32_e32 v36, v4, v3
	v_pk_mul_f32 v[4:5], v[80:81], v[2:3] op_sel_hi:[1,0]
	v_pk_mul_f32 v[28:29], v[82:83], v[2:3] op_sel_hi:[1,0]
	v_pk_fma_f32 v[32:33], v[8:9], v[0:1], v[4:5] op_sel_hi:[1,0,1] neg_lo:[0,0,1] neg_hi:[0,0,1]
	v_pk_mul_f32 v[4:5], v[72:73], v[2:3] op_sel_hi:[1,0]
	v_pk_fma_f32 v[28:29], v[10:11], v[0:1], v[28:29] op_sel_hi:[1,0,1] neg_lo:[0,0,1] neg_hi:[0,0,1]
	v_pk_fma_f32 v[10:11], v[68:69], v[0:1], v[4:5] op_sel_hi:[1,0,1] neg_lo:[0,0,1] neg_hi:[0,0,1]
	v_pk_mul_f32 v[2:3], v[74:75], v[2:3] op_sel_hi:[1,0]
	v_mov_b32_e32 v4, v11
	v_mov_b32_e32 v5, v33
	v_pk_fma_f32 v[8:9], v[70:71], v[0:1], v[2:3] op_sel_hi:[1,0,1] neg_lo:[0,0,1] neg_hi:[0,0,1]
	v_mov_b32_e32 v2, v10
	v_mov_b32_e32 v3, v32
	v_pk_mul_f32 v[4:5], v[4:5], v[4:5]
	s_nop 0
	v_pk_fma_f32 v[2:3], v[2:3], v[2:3], v[4:5]
	v_mov_b32_e32 v4, v8
	v_mov_b32_e32 v5, v28
	v_pk_fma_f32 v[2:3], v[4:5], v[4:5], v[2:3]
	v_mov_b32_e32 v4, v9
	v_mov_b32_e32 v5, v29
	v_pk_fma_f32 v[2:3], v[4:5], v[4:5], v[2:3]
	s_nop 0
	v_add_f32_e32 v0, v3, v36
	v_add_f32_e32 v0, v2, v0
	ds_bpermute_b32 v2, v136, v0
	s_waitcnt lgkmcnt(0)
	v_add_f32_e32 v0, v0, v2
	ds_bpermute_b32 v2, v135, v0
	s_waitcnt lgkmcnt(0)
	v_add_f32_e32 v0, v0, v2
	v_fmamk_f32 v0, v0, 0x3c000000, v144
	v_rsq_f32_e32 v0, v0
	v_lshl_add_u64 v[2:3], v[120:121], 1, s[6:7]
	v_mul_f32_e32 v36, v119, v0
	v_lshlrev_b32_e32 v0, 1, v118
	v_lshl_add_u64 v[2:3], v[2:3], 0, v[0:1]
	v_lshlrev_b32_e32 v0, 3, v134
	v_lshl_add_u64 v[38:39], v[2:3], 0, v[0:1]
	global_load_dwordx4 v[218:221], v37, s[92:93]
	global_load_dwordx4 v[222:225], v37, s[92:93] offset:64
	global_load_dwordx4 v[226:229], v37, s[92:93] offset:128
	global_load_dwordx4 v[230:233], v37, s[92:93] offset:192
	global_load_dwordx4 v[234:237], v37, s[92:93] offset:256
	global_load_dwordx4 v[238:241], v37, s[92:93] offset:320
	global_load_dwordx4 v[242:245], v37, s[92:93] offset:384
	global_load_dwordx4 v[246:249], v37, s[92:93] offset:448
	v_pk_mul_f32 v[12:13], v[12:13], v[36:37] op_sel_hi:[1,0]
	v_pk_mul_f32 v[6:7], v[6:7], v[36:37] op_sel_hi:[1,0]
	v_pk_mul_f32 v[8:9], v[8:9], v[36:37] op_sel_hi:[1,0]
	s_waitcnt vmcnt(0)
	v_pk_mul_f32 v[4:5], v[220:221], v[6:7]
	v_pk_mul_f32 v[2:3], v[218:219], v[12:13]
	v_pk_mul_f32 v[6:7], v[22:23], v[36:37] op_sel_hi:[1,0]
	v_cvt_pk_bf16_f32 v2, v2, v3
	v_cvt_pk_bf16_f32 v3, v4, v5
	global_store_dwordx2 v[38:39], v[2:3], off
	v_pk_mul_f32 v[12:13], v[14:15], v[36:37] op_sel_hi:[1,0]
	v_pk_mul_f32 v[2:3], v[222:223], v[6:7]
	v_pk_mul_f32 v[4:5], v[224:225], v[12:13]
	v_cvt_pk_bf16_f32 v2, v2, v3
	v_cvt_pk_bf16_f32 v3, v4, v5
	global_store_dwordx2 v[38:39], v[2:3], off offset:32
	v_pk_mul_f32 v[6:7], v[44:45], v[36:37] op_sel_hi:[1,0]
	v_pk_mul_f32 v[12:13], v[26:27], v[36:37] op_sel_hi:[1,0]
	v_pk_mul_f32 v[2:3], v[226:227], v[6:7]
	v_pk_mul_f32 v[4:5], v[228:229], v[12:13]
	v_cvt_pk_bf16_f32 v2, v2, v3
	v_cvt_pk_bf16_f32 v3, v4, v5
	global_store_dwordx2 v[38:39], v[2:3], off offset:64
	v_pk_mul_f32 v[6:7], v[24:25], v[36:37] op_sel_hi:[1,0]
	v_pk_mul_f32 v[12:13], v[20:21], v[36:37] op_sel_hi:[1,0]
	v_pk_mul_f32 v[2:3], v[230:231], v[6:7]
	v_pk_mul_f32 v[4:5], v[232:233], v[12:13]
	v_cvt_pk_bf16_f32 v2, v2, v3
	v_cvt_pk_bf16_f32 v3, v4, v5
	global_store_dwordx2 v[38:39], v[2:3], off offset:96
	v_pk_mul_f32 v[6:7], v[34:35], v[36:37] op_sel_hi:[1,0]
	v_pk_mul_f32 v[12:13], v[30:31], v[36:37] op_sel_hi:[1,0]
	v_pk_mul_f32 v[2:3], v[234:235], v[6:7]
	v_pk_mul_f32 v[4:5], v[236:237], v[12:13]
	v_cvt_pk_bf16_f32 v2, v2, v3
	v_cvt_pk_bf16_f32 v3, v4, v5
	global_store_dwordx2 v[38:39], v[2:3], off offset:128
	v_pk_mul_f32 v[6:7], v[16:17], v[36:37] op_sel_hi:[1,0]
	v_pk_mul_f32 v[12:13], v[18:19], v[36:37] op_sel_hi:[1,0]
	v_pk_mul_f32 v[2:3], v[238:239], v[6:7]
	v_pk_mul_f32 v[4:5], v[240:241], v[12:13]
	v_cvt_pk_bf16_f32 v2, v2, v3
	v_cvt_pk_bf16_f32 v3, v4, v5
	global_store_dwordx2 v[38:39], v[2:3], off offset:160
	v_pk_mul_f32 v[6:7], v[32:33], v[36:37] op_sel_hi:[1,0]
	v_pk_mul_f32 v[12:13], v[28:29], v[36:37] op_sel_hi:[1,0]
	v_pk_mul_f32 v[2:3], v[242:243], v[6:7]
	v_pk_mul_f32 v[4:5], v[244:245], v[12:13]
	v_cvt_pk_bf16_f32 v2, v2, v3
	v_cvt_pk_bf16_f32 v3, v4, v5
	global_store_dwordx2 v[38:39], v[2:3], off offset:192
	v_pk_mul_f32 v[6:7], v[10:11], v[36:37] op_sel_hi:[1,0]
	v_pk_mul_f32 v[4:5], v[248:249], v[8:9]
	v_pk_mul_f32 v[2:3], v[246:247], v[6:7]
	s_nop 0
	v_cvt_pk_bf16_f32 v2, v2, v3
	v_cvt_pk_bf16_f32 v3, v4, v5
	global_store_dwordx2 v[38:39], v[2:3], off offset:224

.LBB0_136:
	s_or_b64 exec, exec, s[6:7]
	v_and_b32_e32 v44, 3, v2
	v_mul_u32_u24_e32 v0, 0x180000, v44
	v_readlane_b32 s6, v217, 37
	v_lshlrev_b32_e32 v0, 1, v0
	v_readlane_b32 s7, v217, 38
	v_bfe_i32 v5, v56, 27, 1
	v_lshrrev_b32_e32 v5, 22, v5
	v_lshl_add_u64 v[2:3], s[6:7], 0, v[0:1]
	v_lshlrev_b32_e32 v0, 1, v60
	v_lshl_add_u64 v[2:3], v[2:3], 0, v[0:1]
	v_lshlrev_b32_e32 v0, 4, v56
	v_add_u32_e32 v5, v0, v5
	v_and_b32_e32 v5, 0xfffffc00, v5
	v_ashrrev_i32_e32 v4, 31, v56
	v_sub_u32_e32 v5, v0, v5
	v_lshrrev_b32_e32 v4, 26, v4
	v_lshrrev_b32_e32 v6, 4, v5
	v_add_u32_e32 v4, v56, v4
	v_bitop3_b32 v6, v6, v5, 32 bitop3:0x6c
	v_ashrrev_i32_e32 v5, 31, v5
	v_ashrrev_i32_e32 v4, 6, v4
	v_lshrrev_b32_e32 v5, 26, v5
	v_lshlrev_b32_e32 v7, 3, v4
	v_add_u32_e32 v5, v6, v5
	v_and_b32_e32 v7, -16, v7
	v_ashrrev_i32_e32 v5, 6, v5
	v_add_u32_e32 v12, v5, v7
	v_mul_i32_i24_e32 v5, 64, v5
	v_lshlrev_b32_e32 v4, 5, v4
	v_sub_u32_e32 v5, v6, v5
	v_and_b32_e32 v4, 32, v4
	v_ashrrev_i16_sdwa v5, v146, sext(v5) dst_sel:DWORD dst_unused:UNUSED_PAD src0_sel:DWORD src1_sel:BYTE_0
	s_movk_i32 s8, 0x3000
	v_add_u32_e32 v45, 0, v0
	v_add_u32_sdwa v34, v4, sext(v5) dst_sel:DWORD dst_unused:UNUSED_PAD src0_sel:DWORD src1_sel:WORD_0
	v_mad_i64_i32 v[4:5], s[6:7], v12, s8, v[2:3]
	v_add_u32_e32 v6, 0x8000, v45
	v_add_u32_e32 v13, 0x2000, v0
	v_readfirstlane_b32 s6, v6
	v_ashrrev_i32_e32 v6, 31, v13
	v_lshrrev_b32_e32 v6, 22, v6
	v_add_u32_e32 v6, v13, v6
	v_ashrrev_i32_e32 v6, 10, v6
	v_mul_i32_i24_e32 v7, 0x400, v6
	v_sub_u32_e32 v7, v13, v7
	v_lshrrev_b32_e32 v8, 4, v7
	v_bitop3_b32 v7, v8, v7, 32 bitop3:0x6c
	v_ashrrev_i32_e32 v9, 31, v7
	v_lshrrev_b32_e32 v9, 26, v9
	v_lshlrev_b32_e32 v8, 3, v6
	v_add_u32_e32 v9, v7, v9
	v_and_b32_e32 v8, -16, v8
	v_ashrrev_i32_e32 v10, 6, v9
	v_add_u32_e32 v14, v10, v8
	v_and_b32_e32 v8, 0xc0, v9
	v_lshlrev_b32_e32 v6, 5, v6
	v_sub_u32_e32 v7, v7, v8
	v_and_b32_e32 v6, 32, v6
	v_ashrrev_i16_sdwa v7, v146, sext(v7) dst_sel:DWORD dst_unused:UNUSED_PAD src0_sel:DWORD src1_sel:BYTE_0
	s_mov_b32 m0, s6
	v_add_u32_sdwa v36, v6, sext(v7) dst_sel:DWORD dst_unused:UNUSED_PAD src0_sel:DWORD src1_sel:WORD_0
	v_mad_i64_i32 v[6:7], s[6:7], v14, s8, v[2:3]
	v_add_u32_e32 v8, 0xa000, v45
	v_add_u32_e32 v15, 0x4000, v0
	v_readfirstlane_b32 s6, v8
	v_ashrrev_i32_e32 v8, 31, v15
	v_lshrrev_b32_e32 v8, 22, v8
	v_add_u32_e32 v8, v15, v8
	v_ashrrev_i32_e32 v8, 10, v8
	v_mul_i32_i24_e32 v9, 0x400, v8
	v_sub_u32_e32 v9, v15, v9
	v_lshrrev_b32_e32 v10, 4, v9
	v_bitop3_b32 v9, v10, v9, 32 bitop3:0x6c
	v_ashrrev_i32_e32 v11, 31, v9
	v_lshrrev_b32_e32 v11, 26, v11
	v_add_u32_e32 v11, v9, v11
	v_ashrrev_i32_e32 v16, 6, v11
	v_and_b32_e32 v11, 0xc0, v11
	v_lshlrev_b32_e32 v10, 3, v8
	v_lshlrev_b32_e32 v8, 5, v8
	v_sub_u32_e32 v9, v9, v11
	v_ashrrev_i32_e32 v35, 31, v34
	v_and_b32_e32 v10, -16, v10
	v_and_b32_e32 v8, 32, v8
	v_ashrrev_i16_sdwa v9, v146, sext(v9) dst_sel:DWORD dst_unused:UNUSED_PAD src0_sel:DWORD src1_sel:BYTE_0
	v_lshl_add_u64 v[4:5], v[34:35], 1, v[4:5]
	v_add_u32_e32 v10, v16, v10
	v_add_u32_sdwa v8, v8, sext(v9) dst_sel:DWORD dst_unused:UNUSED_PAD src0_sel:DWORD src1_sel:WORD_0
	global_load_lds_dwordx4 v[4:5], off
	s_mov_b32 m0, s6
	v_mad_i64_i32 v[10:11], s[6:7], v10, s8, v[2:3]
	v_ashrrev_i32_e32 v9, 31, v8
	v_lshl_add_u64 v[8:9], v[8:9], 1, v[10:11]
	v_add_u32_e32 v10, 0xc000, v45
	v_add_u32_e32 v16, 0x6000, v0
	v_readfirstlane_b32 s6, v10
	v_ashrrev_i32_e32 v10, 31, v16
	v_lshrrev_b32_e32 v10, 22, v10
	v_add_u32_e32 v10, v16, v10
	v_ashrrev_i32_e32 v10, 10, v10
	v_mul_i32_i24_e32 v11, 0x400, v10
	v_sub_u32_e32 v11, v16, v11
	v_lshrrev_b32_e32 v17, 4, v11
	v_bitop3_b32 v11, v17, v11, 32 bitop3:0x6c
	v_ashrrev_i32_e32 v18, 31, v11
	v_lshrrev_b32_e32 v18, 26, v18
	v_add_u32_e32 v18, v11, v18
	v_ashrrev_i32_e32 v19, 6, v18
	v_and_b32_e32 v18, 0xc0, v18
	v_lshlrev_b32_e32 v17, 3, v10
	v_lshlrev_b32_e32 v10, 5, v10
	v_sub_u32_e32 v11, v11, v18
	v_ashrrev_i32_e32 v37, 31, v36
	v_and_b32_e32 v17, -16, v17
	v_and_b32_e32 v10, 32, v10
	v_ashrrev_i16_sdwa v11, v146, sext(v11) dst_sel:DWORD dst_unused:UNUSED_PAD src0_sel:DWORD src1_sel:BYTE_0
	v_lshl_add_u64 v[6:7], v[36:37], 1, v[6:7]
	v_add_u32_e32 v17, v19, v17
	v_add_u32_sdwa v10, v10, sext(v11) dst_sel:DWORD dst_unused:UNUSED_PAD src0_sel:DWORD src1_sel:WORD_0
	global_load_lds_dwordx4 v[6:7], off
	s_mov_b32 m0, s6
	v_mad_i64_i32 v[2:3], s[6:7], v17, s8, v[2:3]
	v_ashrrev_i32_e32 v11, 31, v10
	v_lshl_add_u64 v[2:3], v[10:11], 1, v[2:3]
	v_add_u32_e32 v10, 0xe000, v45
	global_load_lds_dwordx4 v[8:9], off
	v_readfirstlane_b32 s6, v10
	s_mov_b32 m0, s6
	s_add_i32 s6, 0, 0x10000
	v_add_u32_e32 v0, s6, v0
	global_load_lds_dwordx4 v[2:3], off
	v_readfirstlane_b32 s7, v0
	v_add_u32_e32 v0, s6, v13
	v_lshl_add_u64 v[4:5], v[4:5], 0, s[30:31]
	s_mov_b32 m0, s7
	v_readfirstlane_b32 s7, v0
	v_add_u32_e32 v0, s6, v15
	global_load_lds_dwordx4 v[4:5], off
	v_lshl_add_u64 v[4:5], v[6:7], 0, s[30:31]
	s_mov_b32 m0, s7
	v_readfirstlane_b32 s7, v0
	v_add_u32_e32 v0, s6, v16
	global_load_lds_dwordx4 v[4:5], off
	v_lshl_add_u64 v[4:5], v[8:9], 0, s[30:31]
	s_mov_b32 m0, s7
	v_readfirstlane_b32 s7, v0
	v_or_b32_e32 v54, s20, v44
	global_load_lds_dwordx4 v[4:5], off
	v_lshl_add_u64 v[2:3], v[2:3], 0, s[30:31]
	s_mov_b32 m0, s7
	v_ashrrev_i32_e32 v55, 31, v54
	v_readlane_b32 s68, v214, 40
	global_load_lds_dwordx4 v[2:3], off
	v_lshlrev_b64 v[2:3], 16, v[54:55]
	v_readlane_b32 s78, v214, 50
	v_readlane_b32 s79, v214, 51
	s_waitcnt vmcnt(0) lgkmcnt(0)
	s_barrier
	v_lshl_add_u64 v[10:11], s[78:79], 0, v[2:3]
	v_lshlrev_b32_e32 v2, 7, v12
	v_ashrrev_i32_e32 v3, 31, v2
	v_lshl_add_u64 v[2:3], v[2:3], 2, v[10:11]
	v_lshl_add_u64 v[22:23], v[34:35], 2, v[2:3]
	global_load_dwordx4 v[2:5], v[22:23], off
	global_load_dwordx4 v[6:9], v[22:23], off offset:16
	v_lshlrev_b32_e32 v12, 7, v14
	v_ashrrev_i32_e32 v13, 31, v12
	v_lshl_add_u64 v[10:11], v[12:13], 2, v[10:11]
	v_lshl_add_u64 v[30:31], v[36:37], 2, v[10:11]
	global_load_dwordx4 v[10:13], v[30:31], off
	global_load_dwordx4 v[14:17], v[30:31], off offset:16
	global_load_dwordx4 v[18:21], v[22:23], off offset:256
	s_nop 0
	global_load_dwordx4 v[22:25], v[22:23], off offset:272
	s_nop 0
	global_load_dwordx4 v[26:29], v[30:31], off offset:256
	s_nop 0
	global_load_dwordx4 v[30:33], v[30:31], off offset:272
	v_lshlrev_b32_e32 v0, 2, v34
	s_add_i32 s7, 0, 0x24000
	v_add_u32_e32 v37, s7, v0
	ds_read2_b32 v[34:35], v37 offset1:1
	ds_read2_b32 v[38:39], v37 offset0:2 offset1:3
	ds_read2_b32 v[40:41], v37 offset0:4 offset1:5
	ds_read2_b32 v[42:43], v37 offset0:6 offset1:7
	v_bfe_u32 v58, v56, 4, 2
	v_lshlrev_b32_e32 v57, 8, v44
	v_readlane_b32 s69, v214, 41
	v_readlane_b32 s70, v214, 42
	v_readlane_b32 s71, v214, 43
	v_readlane_b32 s72, v214, 44
	v_readlane_b32 s73, v214, 45
	v_readlane_b32 s74, v214, 46
	v_readlane_b32 s75, v214, 47
	v_readlane_b32 s76, v214, 48
	v_readlane_b32 s77, v214, 49
	v_readlane_b32 s80, v214, 52
	v_readlane_b32 s81, v214, 53
	v_readlane_b32 s82, v214, 54
	v_readlane_b32 s83, v214, 55
	s_waitcnt vmcnt(7) lgkmcnt(3)
	v_pk_mul_f32 v[2:3], v[2:3], v[34:35]
	s_waitcnt lgkmcnt(2)
	v_pk_mul_f32 v[4:5], v[4:5], v[38:39]
	v_cvt_pk_bf16_f32 v2, v2, v3
	v_cvt_pk_bf16_f32 v3, v4, v5
	s_waitcnt vmcnt(6) lgkmcnt(1)
	v_pk_mul_f32 v[4:5], v[6:7], v[40:41]
	s_waitcnt lgkmcnt(0)
	v_pk_mul_f32 v[6:7], v[8:9], v[42:43]
	v_cvt_pk_bf16_f32 v4, v4, v5
	v_cvt_pk_bf16_f32 v5, v6, v7
	v_lshlrev_b32_e32 v34, 2, v36
	ds_write_b128 v45, v[2:5]
	v_add_u32_e32 v8, s7, v34
	ds_read2_b32 v[2:3], v8 offset1:1
	ds_read2_b32 v[4:5], v8 offset0:2 offset1:3
	ds_read2_b32 v[6:7], v8 offset0:4 offset1:5
	ds_read2_b32 v[8:9], v8 offset0:6 offset1:7
	v_readlane_b32 s7, v214, 35
	s_waitcnt vmcnt(5) lgkmcnt(2)
	v_pk_mul_f32 v[4:5], v[12:13], v[4:5]
	v_pk_mul_f32 v[2:3], v[10:11], v[2:3]
	v_add_u32_e32 v0, s7, v0
	v_cvt_pk_bf16_f32 v2, v2, v3
	v_cvt_pk_bf16_f32 v3, v4, v5
	s_waitcnt vmcnt(4) lgkmcnt(1)
	v_pk_mul_f32 v[4:5], v[14:15], v[6:7]
	s_waitcnt lgkmcnt(0)
	v_pk_mul_f32 v[6:7], v[16:17], v[8:9]
	v_cvt_pk_bf16_f32 v4, v4, v5
	v_cvt_pk_bf16_f32 v5, v6, v7
	ds_write_b128 v45, v[2:5] offset:8192
	ds_read2_b32 v[2:3], v0 offset1:1
	ds_read2_b32 v[4:5], v0 offset0:2 offset1:3
	ds_read2_b32 v[6:7], v0 offset0:4 offset1:5
	ds_read2_b32 v[8:9], v0 offset0:6 offset1:7
	v_add_u32_e32 v0, s7, v34
	v_and_b32_e32 v10, 15, v56
	s_waitcnt vmcnt(3) lgkmcnt(2)
	v_pk_mul_f32 v[4:5], v[20:21], v[4:5]
	v_pk_mul_f32 v[2:3], v[18:19], v[2:3]
	s_movk_i32 s7, 0x6000
	v_cvt_pk_bf16_f32 v2, v2, v3
	v_cvt_pk_bf16_f32 v3, v4, v5
	s_waitcnt vmcnt(2) lgkmcnt(1)
	v_pk_mul_f32 v[4:5], v[22:23], v[6:7]
	s_waitcnt lgkmcnt(0)
	v_pk_mul_f32 v[6:7], v[24:25], v[8:9]
	v_cvt_pk_bf16_f32 v4, v4, v5
	v_cvt_pk_bf16_f32 v5, v6, v7
	ds_write_b128 v45, v[2:5] offset:16384
	ds_read2_b32 v[2:3], v0 offset1:1
	ds_read2_b32 v[4:5], v0 offset0:2 offset1:3
	ds_read2_b32 v[6:7], v0 offset0:4 offset1:5
	ds_read2_b32 v[8:9], v0 offset0:6 offset1:7
	v_ashrrev_i32_e32 v0, 2, v56
	v_and_b32_e32 v0, 0xffffffc0, v0
	s_waitcnt vmcnt(1) lgkmcnt(2)
	v_pk_mul_f32 v[4:5], v[28:29], v[4:5]
	v_pk_mul_f32 v[2:3], v[26:27], v[2:3]
	v_or_b32_e32 v114, v0, v10
	v_cvt_pk_bf16_f32 v2, v2, v3
	v_cvt_pk_bf16_f32 v3, v4, v5
	s_waitcnt vmcnt(0) lgkmcnt(1)
	v_pk_mul_f32 v[4:5], v[30:31], v[6:7]
	s_waitcnt lgkmcnt(0)
	v_pk_mul_f32 v[6:7], v[32:33], v[8:9]
	v_cvt_pk_bf16_f32 v4, v4, v5
	v_cvt_pk_bf16_f32 v5, v6, v7
	ds_write_b128 v45, v[2:5] offset:24576
	v_lshlrev_b32_e32 v2, 4, v58
	v_lshlrev_b32_e32 v4, 2, v56
	v_lshl_or_b32 v3, v10, 6, v2
	v_lshlrev_b32_e32 v0, 7, v0
	v_and_b32_e32 v4, 32, v4
	v_bitop3_b32 v0, v3, v0, v4 bitop3:0xde
	v_lshlrev_b32_e32 v3, 6, v56
	v_and_b32_e32 v3, 0x3c0, v3
	v_lshlrev_b32_e32 v5, 7, v56
	v_bitop3_b32 v2, v3, v4, v2 bitop3:0x36
	s_waitcnt vmcnt(0)
	s_waitcnt lgkmcnt(0)
	s_barrier
	v_add_u32_e32 v46, 0, v0
	v_and_or_b32 v59, v5, s7, v2
	ds_read_b128 v[2:5], v46 offset:0
	ds_read_b128 v[6:9], v46 offset:2048
	ds_read_b128 v[10:13], v46 offset:4096
	s_add_i32 s7, 0, 0x8000
	ds_read_b128 v[14:17], v46 offset:6144
	v_add_u32_e32 v61, s7, v59
	ds_read_b128 v[18:21], v61 offset:0
	ds_read_b128 v[22:25], v61 offset:2048
	ds_read_b128 v[26:29], v61 offset:4096
	ds_read_b128 v[30:33], v61 offset:6144
	ds_read_b128 v[34:37], v46 offset:1024
	ds_read_b128 v[38:41], v46 offset:3072
	ds_read_b128 v[42:45], v46 offset:5120
	ds_read_b128 v[46:49], v46 offset:7168
	ds_read_b128 v[50:53], v61 offset:1024
	ds_read_b128 v[62:65], v61 offset:3072
	ds_read_b128 v[66:69], v61 offset:5120
	ds_read_b128 v[70:73], v61 offset:7168
	s_waitcnt lgkmcnt(8)
	s_nop 0
	v_mfma_f32_16x16x32_bf16 v[74:77], v[18:21], v[2:5], 0
	v_mfma_f32_16x16x32_bf16 v[78:81], v[22:25], v[2:5], 0
	v_mfma_f32_16x16x32_bf16 v[82:85], v[26:29], v[2:5], 0
	v_mfma_f32_16x16x32_bf16 v[2:5], v[30:33], v[2:5], 0
	v_mfma_f32_16x16x32_bf16 v[86:89], v[18:21], v[6:9], 0
	v_mfma_f32_16x16x32_bf16 v[90:93], v[22:25], v[6:9], 0
	v_mfma_f32_16x16x32_bf16 v[94:97], v[26:29], v[6:9], 0
	v_mfma_f32_16x16x32_bf16 v[6:9], v[30:33], v[6:9], 0
	v_mfma_f32_16x16x32_bf16 v[98:101], v[18:21], v[10:13], 0
	v_mfma_f32_16x16x32_bf16 v[102:105], v[22:25], v[10:13], 0
	v_mfma_f32_16x16x32_bf16 v[106:109], v[26:29], v[10:13], 0
	v_mfma_f32_16x16x32_bf16 v[10:13], v[30:33], v[10:13], 0
	v_mfma_f32_16x16x32_bf16 v[18:21], v[18:21], v[14:17], 0
	v_mfma_f32_16x16x32_bf16 v[22:25], v[22:25], v[14:17], 0
	v_mfma_f32_16x16x32_bf16 v[26:29], v[26:29], v[14:17], 0
	v_mfma_f32_16x16x32_bf16 v[14:17], v[30:33], v[14:17], 0
	s_waitcnt lgkmcnt(0)
	v_mfma_f32_16x16x32_bf16 v[2:5], v[70:73], v[34:37], v[2:5]
	v_mfma_f32_16x16x32_bf16 v[30:33], v[50:53], v[34:37], v[74:77]
	v_mfma_f32_16x16x32_bf16 v[74:77], v[62:65], v[34:37], v[78:81]
	v_mfma_f32_16x16x32_bf16 v[78:81], v[66:69], v[34:37], v[82:85]
	v_mfma_f32_16x16x32_bf16 v[34:37], v[50:53], v[38:41], v[86:89]
	v_mfma_f32_16x16x32_bf16 v[82:85], v[62:65], v[38:41], v[90:93]
	v_mfma_f32_16x16x32_bf16 v[86:89], v[66:69], v[38:41], v[94:97]
	v_mfma_f32_16x16x32_bf16 v[6:9], v[70:73], v[38:41], v[6:9]
	v_mfma_f32_16x16x32_bf16 v[38:41], v[50:53], v[42:45], v[98:101]
	v_mfma_f32_16x16x32_bf16 v[90:93], v[62:65], v[42:45], v[102:105]
	v_mfma_f32_16x16x32_bf16 v[94:97], v[66:69], v[42:45], v[106:109]
	v_mfma_f32_16x16x32_bf16 v[10:13], v[70:73], v[42:45], v[10:13]
	v_mfma_f32_16x16x32_bf16 v[18:21], v[50:53], v[46:49], v[18:21]
	v_mfma_f32_16x16x32_bf16 v[22:25], v[62:65], v[46:49], v[22:25]
	v_mfma_f32_16x16x32_bf16 v[26:29], v[66:69], v[46:49], v[26:29]
	v_mfma_f32_16x16x32_bf16 v[14:17], v[70:73], v[46:49], v[14:17]
	s_add_i32 s7, 0, 0x4000
	v_add_u32_e32 v0, s7, v0
	ds_read_b128 v[42:45], v0 offset:0
	ds_read_b128 v[46:49], v0 offset:2048
	ds_read_b128 v[50:53], v0 offset:4096
	ds_read_b128 v[62:65], v0 offset:6144
	v_add_u32_e32 v59, s6, v59
	ds_read_b128 v[66:69], v59 offset:0
	ds_read_b128 v[70:73], v59 offset:2048
	ds_read_b128 v[98:101], v59 offset:4096
	ds_read_b128 v[102:105], v59 offset:6144
	ds_read_b128 v[106:109], v0 offset:1024
	ds_read_b128 v[110:113], v0 offset:3072
	ds_read_b128 v[120:123], v0 offset:5120
	ds_read_b128 v[124:127], v0 offset:7168
	ds_read_b128 v[134:137], v59 offset:1024
	ds_read_b128 v[138:141], v59 offset:3072
	ds_read_b128 v[162:165], v59 offset:5120
	ds_read_b128 v[166:169], v59 offset:7168
	s_waitcnt lgkmcnt(8)
	s_nop 0
	v_mfma_f32_16x16x32_bf16 v[2:5], v[102:105], v[42:45], v[2:5]
	v_mfma_f32_16x16x32_bf16 v[30:33], v[66:69], v[42:45], v[30:33]
	v_mfma_f32_16x16x32_bf16 v[74:77], v[70:73], v[42:45], v[74:77]
	v_mfma_f32_16x16x32_bf16 v[78:81], v[98:101], v[42:45], v[78:81]
	v_mfma_f32_16x16x32_bf16 v[34:37], v[66:69], v[46:49], v[34:37]
	v_mfma_f32_16x16x32_bf16 v[42:45], v[70:73], v[46:49], v[82:85]
	v_mfma_f32_16x16x32_bf16 v[82:85], v[98:101], v[46:49], v[86:89]
	v_mfma_f32_16x16x32_bf16 v[6:9], v[102:105], v[46:49], v[6:9]
	v_mfma_f32_16x16x32_bf16 v[86:89], v[66:69], v[50:53], v[38:41]
	v_mfma_f32_16x16x32_bf16 v[90:93], v[70:73], v[50:53], v[90:93]
	v_mfma_f32_16x16x32_bf16 v[94:97], v[98:101], v[50:53], v[94:97]
	v_mfma_f32_16x16x32_bf16 v[10:13], v[102:105], v[50:53], v[10:13]
	v_mfma_f32_16x16x32_bf16 v[66:69], v[66:69], v[62:65], v[18:21]
	v_mfma_f32_16x16x32_bf16 v[70:73], v[70:73], v[62:65], v[22:25]
	v_mfma_f32_16x16x32_bf16 v[98:101], v[98:101], v[62:65], v[26:29]
	v_mfma_f32_16x16x32_bf16 v[62:65], v[102:105], v[62:65], v[14:17]
	s_waitcnt lgkmcnt(0)
	v_mfma_f32_16x16x32_bf16 v[50:53], v[166:169], v[106:109], v[2:5]
	v_mfma_f32_16x16x32_bf16 v[2:5], v[166:169], v[124:127], v[62:65]
	v_mfma_f32_16x16x32_bf16 v[102:105], v[134:137], v[106:109], v[30:33]
	v_mfma_f32_16x16x32_bf16 v[74:77], v[138:141], v[106:109], v[74:77]
	v_mfma_f32_16x16x32_bf16 v[78:81], v[162:165], v[106:109], v[78:81]
	v_mfma_f32_16x16x32_bf16 v[46:49], v[134:137], v[110:113], v[34:37]
	v_mfma_f32_16x16x32_bf16 v[42:45], v[138:141], v[110:113], v[42:45]
	v_mfma_f32_16x16x32_bf16 v[38:41], v[162:165], v[110:113], v[82:85]
	v_mfma_f32_16x16x32_bf16 v[34:37], v[166:169], v[110:113], v[6:9]
	v_mfma_f32_16x16x32_bf16 v[30:33], v[134:137], v[120:123], v[86:89]
	v_mfma_f32_16x16x32_bf16 v[26:29], v[138:141], v[120:123], v[90:93]
	v_mfma_f32_16x16x32_bf16 v[22:25], v[162:165], v[120:123], v[94:97]
	v_mfma_f32_16x16x32_bf16 v[18:21], v[166:169], v[120:123], v[10:13]
	v_mfma_f32_16x16x32_bf16 v[14:17], v[134:137], v[124:127], v[66:69]
	v_mfma_f32_16x16x32_bf16 v[10:13], v[138:141], v[124:127], v[70:73]
	v_mfma_f32_16x16x32_bf16 v[6:9], v[162:165], v[124:127], v[98:101]
	v_lshlrev_b64 v[54:55], 9, v[54:55]
	v_lshl_add_u64 v[54:55], s[80:81], 0, v[54:55]
	v_ashrrev_i32_e32 v115, 31, v114
	v_and_or_b32 v0, v56, s57, v57
	v_lshl_add_u64 v[56:57], v[114:115], 2, v[54:55]
	v_add_u32_e32 v54, v114, v60
	v_ashrrev_i32_e32 v55, 31, v54
	v_readlane_b32 s8, v217, 39
	v_lshl_or_b32 v0, v58, 2, v0
	v_lshlrev_b64 v[60:61], 11, v[54:55]
	v_readlane_b32 s9, v217, 40
	v_lshlrev_b32_e32 v59, 2, v0
	v_readlane_b32 s6, v217, 24
	v_lshl_add_u64 v[64:65], s[8:9], 0, v[60:61]
	v_lshlrev_b32_e32 v0, 1, v0
	v_readlane_b32 s7, v217, 25
	v_lshl_add_u64 v[64:65], v[64:65], 0, v[0:1]
	v_lshl_add_u64 v[66:67], s[6:7], 0, v[60:61]
	v_lshl_add_u64 v[66:67], v[66:67], 0, v[0:1]
	s_mov_b64 vcc, 0x8000
	global_load_dword v250, v[56:57], off
	global_load_dword v252, v[56:57], off offset:64
	global_load_dword v254, v[56:57], off offset:128
	global_load_dword v70, v[56:57], off offset:192
	global_load_dwordx4 v[106:109], v59, s[86:87]
	global_load_dwordx4 v[110:113], v59, s[86:87] offset:64
	global_load_dwordx4 v[120:123], v59, s[86:87] offset:128
	global_load_dwordx4 v[124:127], v59, s[86:87] offset:192
	global_load_dwordx2 v[218:219], v[64:65], off
	global_load_dwordx2 v[220:221], v[64:65], off offset:32
	global_load_dwordx2 v[222:223], v[64:65], off offset:64
	global_load_dwordx2 v[224:225], v[64:65], off offset:96
	v_lshl_add_u64 v[64:65], v[64:65], 0, vcc
	global_load_dwordx2 v[226:227], v[64:65], off
	global_load_dwordx2 v[228:229], v[64:65], off offset:32
	global_load_dwordx2 v[230:231], v[64:65], off offset:64
	global_load_dwordx2 v[232:233], v[64:65], off offset:96
	v_lshl_add_u64 v[64:65], v[64:65], 0, vcc
	global_load_dwordx2 v[234:235], v[64:65], off
	global_load_dwordx2 v[236:237], v[64:65], off offset:32
	global_load_dwordx2 v[238:239], v[64:65], off offset:64
	global_load_dwordx2 v[240:241], v[64:65], off offset:96
	v_lshl_add_u64 v[64:65], v[64:65], 0, vcc
	global_load_dwordx2 v[242:243], v[64:65], off
	global_load_dwordx2 v[244:245], v[64:65], off offset:32
	global_load_dwordx2 v[246:247], v[64:65], off offset:64
	global_load_dwordx2 v[248:249], v[64:65], off offset:96
	s_waitcnt vmcnt(12)
	v_pk_fma_f32 v[102:103], v[102:103], v[106:107], v[250:251] op_sel_hi:[1,1,0]
	v_pk_fma_f32 v[104:105], v[104:105], v[108:109], v[250:251] op_sel_hi:[1,1,0]
	v_lshlrev_b32_e32 v86, 16, v218
	v_and_b32_e32 v87, 0xffff0000, v218
	v_lshlrev_b32_e32 v88, 16, v219
	v_and_b32_e32 v89, 0xffff0000, v219
	v_pk_mul_f32 v[102:103], v[102:103], v[86:87]
	v_pk_mul_f32 v[104:105], v[104:105], v[88:89]
	s_nop 0
	v_cvt_pk_bf16_f32 v102, v102, v103
	v_cvt_pk_bf16_f32 v103, v104, v105
	global_store_dwordx2 v[66:67], v[102:103], off
	v_pk_fma_f32 v[74:75], v[74:75], v[110:111], v[250:251] op_sel_hi:[1,1,0]
	v_pk_fma_f32 v[76:77], v[76:77], v[112:113], v[250:251] op_sel_hi:[1,1,0]
	v_lshlrev_b32_e32 v90, 16, v220
	v_and_b32_e32 v91, 0xffff0000, v220
	v_lshlrev_b32_e32 v92, 16, v221
	v_and_b32_e32 v93, 0xffff0000, v221
	v_pk_mul_f32 v[74:75], v[74:75], v[90:91]
	v_pk_mul_f32 v[76:77], v[76:77], v[92:93]
	s_nop 0
	v_cvt_pk_bf16_f32 v74, v74, v75
	v_cvt_pk_bf16_f32 v75, v76, v77
	global_store_dwordx2 v[66:67], v[74:75], off offset:32
	v_pk_fma_f32 v[78:79], v[78:79], v[120:121], v[250:251] op_sel_hi:[1,1,0]
	v_pk_fma_f32 v[80:81], v[80:81], v[122:123], v[250:251] op_sel_hi:[1,1,0]
	v_lshlrev_b32_e32 v86, 16, v222
	v_and_b32_e32 v87, 0xffff0000, v222
	v_lshlrev_b32_e32 v88, 16, v223
	v_and_b32_e32 v89, 0xffff0000, v223
	v_pk_mul_f32 v[78:79], v[78:79], v[86:87]
	v_pk_mul_f32 v[80:81], v[80:81], v[88:89]
	s_nop 0
	v_cvt_pk_bf16_f32 v78, v78, v79
	v_cvt_pk_bf16_f32 v79, v80, v81
	global_store_dwordx2 v[66:67], v[78:79], off offset:64
	v_pk_fma_f32 v[50:51], v[50:51], v[124:125], v[250:251] op_sel_hi:[1,1,0]
	v_pk_fma_f32 v[52:53], v[52:53], v[126:127], v[250:251] op_sel_hi:[1,1,0]
	v_lshlrev_b32_e32 v90, 16, v224
	v_and_b32_e32 v91, 0xffff0000, v224
	v_lshlrev_b32_e32 v92, 16, v225
	v_and_b32_e32 v93, 0xffff0000, v225
	v_pk_mul_f32 v[50:51], v[50:51], v[90:91]
	v_pk_mul_f32 v[52:53], v[52:53], v[92:93]
	s_nop 0
	v_cvt_pk_bf16_f32 v50, v50, v51
	v_cvt_pk_bf16_f32 v51, v52, v53
	global_store_dwordx2 v[66:67], v[50:51], off offset:96
	v_lshl_add_u64 v[66:67], v[66:67], 0, vcc
	s_waitcnt vmcnt(12)
	v_pk_fma_f32 v[46:47], v[46:47], v[106:107], v[252:253] op_sel_hi:[1,1,0]
	v_pk_fma_f32 v[48:49], v[48:49], v[108:109], v[252:253] op_sel_hi:[1,1,0]
	v_lshlrev_b32_e32 v86, 16, v226
	v_and_b32_e32 v87, 0xffff0000, v226
	v_lshlrev_b32_e32 v88, 16, v227
	v_and_b32_e32 v89, 0xffff0000, v227
	v_pk_mul_f32 v[46:47], v[46:47], v[86:87]
	v_pk_mul_f32 v[48:49], v[48:49], v[88:89]
	s_nop 0
	v_cvt_pk_bf16_f32 v46, v46, v47
	v_cvt_pk_bf16_f32 v47, v48, v49
	global_store_dwordx2 v[66:67], v[46:47], off
	v_pk_fma_f32 v[42:43], v[42:43], v[110:111], v[252:253] op_sel_hi:[1,1,0]
	v_pk_fma_f32 v[44:45], v[44:45], v[112:113], v[252:253] op_sel_hi:[1,1,0]
	v_lshlrev_b32_e32 v90, 16, v228
	v_and_b32_e32 v91, 0xffff0000, v228
	v_lshlrev_b32_e32 v92, 16, v229
	v_and_b32_e32 v93, 0xffff0000, v229
	v_pk_mul_f32 v[42:43], v[42:43], v[90:91]
	v_pk_mul_f32 v[44:45], v[44:45], v[92:93]
	s_nop 0
	v_cvt_pk_bf16_f32 v42, v42, v43
	v_cvt_pk_bf16_f32 v43, v44, v45
	global_store_dwordx2 v[66:67], v[42:43], off offset:32
	v_pk_fma_f32 v[38:39], v[38:39], v[120:121], v[252:253] op_sel_hi:[1,1,0]
	v_pk_fma_f32 v[40:41], v[40:41], v[122:123], v[252:253] op_sel_hi:[1,1,0]
	v_lshlrev_b32_e32 v86, 16, v230
	v_and_b32_e32 v87, 0xffff0000, v230
	v_lshlrev_b32_e32 v88, 16, v231
	v_and_b32_e32 v89, 0xffff0000, v231
	v_pk_mul_f32 v[38:39], v[38:39], v[86:87]
	v_pk_mul_f32 v[40:41], v[40:41], v[88:89]
	s_nop 0
	v_cvt_pk_bf16_f32 v38, v38, v39
	v_cvt_pk_bf16_f32 v39, v40, v41
	global_store_dwordx2 v[66:67], v[38:39], off offset:64
	v_pk_fma_f32 v[34:35], v[34:35], v[124:125], v[252:253] op_sel_hi:[1,1,0]
	v_pk_fma_f32 v[36:37], v[36:37], v[126:127], v[252:253] op_sel_hi:[1,1,0]
	v_lshlrev_b32_e32 v90, 16, v232
	v_and_b32_e32 v91, 0xffff0000, v232
	v_lshlrev_b32_e32 v92, 16, v233
	v_and_b32_e32 v93, 0xffff0000, v233
	v_pk_mul_f32 v[34:35], v[34:35], v[90:91]
	v_pk_mul_f32 v[36:37], v[36:37], v[92:93]
	s_nop 0
	v_cvt_pk_bf16_f32 v34, v34, v35
	v_cvt_pk_bf16_f32 v35, v36, v37
	global_store_dwordx2 v[66:67], v[34:35], off offset:96
	v_lshl_add_u64 v[66:67], v[66:67], 0, vcc
	s_waitcnt vmcnt(12)
	v_pk_fma_f32 v[30:31], v[30:31], v[106:107], v[254:255] op_sel_hi:[1,1,0]
	v_pk_fma_f32 v[32:33], v[32:33], v[108:109], v[254:255] op_sel_hi:[1,1,0]
	v_lshlrev_b32_e32 v86, 16, v234
	v_and_b32_e32 v87, 0xffff0000, v234
	v_lshlrev_b32_e32 v88, 16, v235
	v_and_b32_e32 v89, 0xffff0000, v235
	v_pk_mul_f32 v[30:31], v[30:31], v[86:87]
	v_pk_mul_f32 v[32:33], v[32:33], v[88:89]
	s_nop 0
	v_cvt_pk_bf16_f32 v30, v30, v31
	v_cvt_pk_bf16_f32 v31, v32, v33
	global_store_dwordx2 v[66:67], v[30:31], off
	v_pk_fma_f32 v[26:27], v[26:27], v[110:111], v[254:255] op_sel_hi:[1,1,0]
	v_pk_fma_f32 v[28:29], v[28:29], v[112:113], v[254:255] op_sel_hi:[1,1,0]
	v_lshlrev_b32_e32 v90, 16, v236
	v_and_b32_e32 v91, 0xffff0000, v236
	v_lshlrev_b32_e32 v92, 16, v237
	v_and_b32_e32 v93, 0xffff0000, v237
	v_pk_mul_f32 v[26:27], v[26:27], v[90:91]
	v_pk_mul_f32 v[28:29], v[28:29], v[92:93]
	s_nop 0
	v_cvt_pk_bf16_f32 v26, v26, v27
	v_cvt_pk_bf16_f32 v27, v28, v29
	global_store_dwordx2 v[66:67], v[26:27], off offset:32
	v_pk_fma_f32 v[22:23], v[22:23], v[120:121], v[254:255] op_sel_hi:[1,1,0]
	v_pk_fma_f32 v[24:25], v[24:25], v[122:123], v[254:255] op_sel_hi:[1,1,0]
	v_lshlrev_b32_e32 v86, 16, v238
	v_and_b32_e32 v87, 0xffff0000, v238
	v_lshlrev_b32_e32 v88, 16, v239
	v_and_b32_e32 v89, 0xffff0000, v239
	v_pk_mul_f32 v[22:23], v[22:23], v[86:87]
	v_pk_mul_f32 v[24:25], v[24:25], v[88:89]
	s_nop 0
	v_cvt_pk_bf16_f32 v22, v22, v23
	v_cvt_pk_bf16_f32 v23, v24, v25
	global_store_dwordx2 v[66:67], v[22:23], off offset:64
	v_pk_fma_f32 v[18:19], v[18:19], v[124:125], v[254:255] op_sel_hi:[1,1,0]
	v_pk_fma_f32 v[20:21], v[20:21], v[126:127], v[254:255] op_sel_hi:[1,1,0]
	v_lshlrev_b32_e32 v90, 16, v240
	v_and_b32_e32 v91, 0xffff0000, v240
	v_lshlrev_b32_e32 v92, 16, v241
	v_and_b32_e32 v93, 0xffff0000, v241
	v_pk_mul_f32 v[18:19], v[18:19], v[90:91]
	v_pk_mul_f32 v[20:21], v[20:21], v[92:93]
	s_nop 0
	v_cvt_pk_bf16_f32 v18, v18, v19
	v_cvt_pk_bf16_f32 v19, v20, v21
	global_store_dwordx2 v[66:67], v[18:19], off offset:96
	v_lshl_add_u64 v[66:67], v[66:67], 0, vcc
	s_waitcnt vmcnt(12)
	v_pk_fma_f32 v[14:15], v[14:15], v[106:107], v[70:71] op_sel_hi:[1,1,0]
	v_pk_fma_f32 v[16:17], v[16:17], v[108:109], v[70:71] op_sel_hi:[1,1,0]
	v_lshlrev_b32_e32 v86, 16, v242
	v_and_b32_e32 v87, 0xffff0000, v242
	v_lshlrev_b32_e32 v88, 16, v243
	v_and_b32_e32 v89, 0xffff0000, v243
	v_pk_mul_f32 v[14:15], v[14:15], v[86:87]
	v_pk_mul_f32 v[16:17], v[16:17], v[88:89]
	s_nop 0
	v_cvt_pk_bf16_f32 v14, v14, v15
	v_cvt_pk_bf16_f32 v15, v16, v17
	global_store_dwordx2 v[66:67], v[14:15], off
	v_pk_fma_f32 v[10:11], v[10:11], v[110:111], v[70:71] op_sel_hi:[1,1,0]
	v_pk_fma_f32 v[12:13], v[12:13], v[112:113], v[70:71] op_sel_hi:[1,1,0]
	v_lshlrev_b32_e32 v90, 16, v244
	v_and_b32_e32 v91, 0xffff0000, v244
	v_lshlrev_b32_e32 v92, 16, v245
	v_and_b32_e32 v93, 0xffff0000, v245
	v_pk_mul_f32 v[10:11], v[10:11], v[90:91]
	v_pk_mul_f32 v[12:13], v[12:13], v[92:93]
	s_nop 0
	v_cvt_pk_bf16_f32 v10, v10, v11
	v_cvt_pk_bf16_f32 v11, v12, v13
	global_store_dwordx2 v[66:67], v[10:11], off offset:32
	v_pk_fma_f32 v[6:7], v[6:7], v[120:121], v[70:71] op_sel_hi:[1,1,0]
	v_pk_fma_f32 v[8:9], v[8:9], v[122:123], v[70:71] op_sel_hi:[1,1,0]
	v_lshlrev_b32_e32 v86, 16, v246
	v_and_b32_e32 v87, 0xffff0000, v246
	v_lshlrev_b32_e32 v88, 16, v247
	v_and_b32_e32 v89, 0xffff0000, v247
	v_pk_mul_f32 v[6:7], v[6:7], v[86:87]
	v_pk_mul_f32 v[8:9], v[8:9], v[88:89]
	s_nop 0
	v_cvt_pk_bf16_f32 v6, v6, v7
	v_cvt_pk_bf16_f32 v7, v8, v9
	global_store_dwordx2 v[66:67], v[6:7], off offset:64
	v_pk_fma_f32 v[2:3], v[2:3], v[124:125], v[70:71] op_sel_hi:[1,1,0]
	v_pk_fma_f32 v[4:5], v[4:5], v[126:127], v[70:71] op_sel_hi:[1,1,0]
	v_lshlrev_b32_e32 v90, 16, v248
	v_and_b32_e32 v91, 0xffff0000, v248
	v_lshlrev_b32_e32 v92, 16, v249
	v_and_b32_e32 v93, 0xffff0000, v249
	v_pk_mul_f32 v[2:3], v[2:3], v[90:91]
	v_pk_mul_f32 v[4:5], v[4:5], v[92:93]
	s_nop 0
	v_cvt_pk_bf16_f32 v2, v2, v3
	v_cvt_pk_bf16_f32 v3, v4, v5
	global_store_dwordx2 v[66:67], v[2:3], off offset:96

.LBB0_150:
	v_sub_f32_e32 v92, v92, v163
	v_sub_f32_e32 v93, v93, v163
	v_exp_f32_e32 v92, v92
	v_exp_f32_e32 v93, v93
	v_sub_f32_e32 v88, v88, v163
	v_sub_f32_e32 v94, v94, v163
	v_exp_f32_e32 v105, v88
	v_sub_f32_e32 v88, v89, v163
	v_exp_f32_e32 v94, v94
	v_sub_f32_e32 v95, v95, v163
	v_exp_f32_e32 v106, v88
	v_sub_f32_e32 v88, v90, v163
	v_exp_f32_e32 v95, v95
	v_exp_f32_e32 v107, v88
	v_sub_f32_e32 v88, v91, v163
	v_exp_f32_e32 v108, v88
	v_cvt_pk_bf16_f32 v88, v92, v93
	v_add_f32_e32 v92, 0, v92
	v_add_f32_e32 v92, v93, v92
	v_add_f32_e32 v92, v94, v92
	v_sub_f32_e32 v72, v100, v163
	v_add_f32_e32 v92, v95, v92
	v_exp_f32_e32 v100, v72
	v_sub_f32_e32 v72, v101, v163
	v_add_f32_e32 v92, v105, v92
	v_exp_f32_e32 v101, v72
	v_sub_f32_e32 v72, v102, v163
	v_add_f32_e32 v92, v106, v92
	v_exp_f32_e32 v102, v72
	v_sub_f32_e32 v72, v103, v163
	v_add_f32_e32 v92, v107, v92
	v_exp_f32_e32 v103, v72
	v_sub_f32_e32 v72, v96, v163
	v_add_f32_e32 v92, v108, v92
	v_exp_f32_e32 v96, v72
	v_sub_f32_e32 v72, v97, v163
	v_add_f32_e32 v92, v100, v92
	v_exp_f32_e32 v97, v72
	v_sub_f32_e32 v72, v98, v163
	v_add_f32_e32 v92, v101, v92
	v_exp_f32_e32 v98, v72
	v_sub_f32_e32 v72, v99, v163
	v_add_f32_e32 v92, v102, v92
	s_waitcnt lgkmcnt(0)
	v_add_f32_e32 v3, v3, v104
	v_add_f32_e32 v0, v0, v2
	v_exp_f32_e32 v99, v72
	v_add_f32_e32 v92, v103, v92
	v_mul_f32_e32 v3, 0x3fb8aa3b, v3
	v_mul_f32_e32 v0, 0x3fb8aa3b, v0
	v_add_f32_e32 v92, v96, v92
	v_exp_f32_e32 v3, v3
	v_exp_f32_e32 v0, v0
	v_add_f32_e32 v92, v97, v92
	v_add_f32_e32 v2, v98, v92
	v_add_f32_e32 v2, v99, v2
	v_cvt_pk_bf16_f32 v91, v107, v108
	v_add_f32_e32 v108, v141, v2
	v_sub_f32_e32 v2, v3, v0
	v_sub_f32_e32 v0, v84, v161
	v_exp_f32_e32 v0, v0
	v_sub_f32_e32 v3, v85, v161
	v_exp_f32_e32 v3, v3
	v_sub_f32_e32 v84, v86, v161
	v_exp_f32_e32 v84, v84
	v_sub_f32_e32 v85, v87, v161
	v_exp_f32_e32 v85, v85
	v_sub_f32_e32 v80, v80, v161
	v_add_f32_e32 v86, 0, v0
	v_exp_f32_e32 v80, v80
	v_sub_f32_e32 v81, v81, v161
	v_add_f32_e32 v86, v3, v86
	v_exp_f32_e32 v81, v81
	v_sub_f32_e32 v82, v82, v161
	v_add_f32_e32 v86, v84, v86
	v_exp_f32_e32 v82, v82
	v_sub_f32_e32 v83, v83, v161
	v_add_f32_e32 v86, v85, v86
	v_exp_f32_e32 v83, v83
	v_sub_f32_e32 v76, v76, v161
	v_add_f32_e32 v86, v80, v86
	v_exp_f32_e32 v76, v76
	v_sub_f32_e32 v77, v77, v161
	v_add_f32_e32 v86, v81, v86
	v_exp_f32_e32 v77, v77
	v_sub_f32_e32 v78, v78, v161
	v_add_f32_e32 v86, v82, v86
	v_exp_f32_e32 v78, v78
	v_sub_f32_e32 v79, v79, v161
	v_sub_f32_e32 v68, v68, v161
	v_add_f32_e32 v86, v83, v86
	v_exp_f32_e32 v79, v79
	v_exp_f32_e32 v87, v68
	v_sub_f32_e32 v68, v69, v161
	v_add_f32_e32 v86, v76, v86
	v_exp_f32_e32 v92, v68
	v_sub_f32_e32 v68, v70, v161
	v_add_f32_e32 v86, v77, v86
	v_exp_f32_e32 v93, v68
	v_sub_f32_e32 v68, v71, v161
	v_cvt_pk_bf16_f32 v89, v94, v95
	v_add_f32_e32 v86, v78, v86
	v_exp_f32_e32 v94, v68
	v_cvt_pk_bf16_f32 v70, v80, v81
	ds_read_b64 v[80:81], v117 offset:0
	v_add_f32_e32 v86, v79, v86
	v_cvt_pk_bf16_f32 v71, v82, v83
	ds_read_b64 v[82:83], v137 offset:0
	v_add_f32_e32 v68, v87, v86
	v_cvt_pk_bf16_f32 v69, v84, v85
	ds_read_b64 v[84:85], v138 offset:0
	v_add_f32_e32 v68, v92, v68
	v_cvt_pk_bf16_f32 v76, v76, v77
	v_cvt_pk_bf16_f32 v77, v78, v79
	v_cvt_pk_bf16_f32 v78, v87, v92
	ds_read_b64 v[86:87], v139 offset:0
	v_add_f32_e32 v68, v93, v68
	v_cvt_pk_bf16_f32 v79, v93, v94
	ds_read_b64 v[92:93], v117 offset:2048
	v_add_f32_e32 v68, v94, v68
	ds_read_b64 v[94:95], v137 offset:2048
	v_cvt_pk_bf16_f32 v74, v96, v97
	ds_read_b64 v[96:97], v138 offset:2048
	v_cvt_pk_bf16_f32 v75, v98, v99
	ds_read_b64 v[98:99], v139 offset:2048
	v_cvt_pk_bf16_f32 v72, v100, v101
	ds_read_b64 v[100:101], v117 offset:4096
	v_cvt_pk_bf16_f32 v73, v102, v103
	ds_read_b64 v[102:103], v137 offset:4096
	v_cvt_pk_bf16_f32 v90, v105, v106
	ds_read_b64 v[104:105], v138 offset:4096
	ds_read_b64 v[106:107], v139 offset:4096
	v_add_f32_e32 v109, v140, v68
	v_cvt_pk_bf16_f32 v68, v0, v3
	s_waitcnt lgkmcnt(8)
	v_mfma_f32_16x16x32_bf16 v[64:67], v[80:83], v[88:91], v[64:67]
	s_nop 0
	v_mfma_f32_16x16x32_bf16 v[80:83], v[80:83], v[68:71], v[60:63]
	v_mfma_f32_16x16x32_bf16 v[60:63], v[84:87], v[72:75], v[64:67]
	v_mfma_f32_16x16x32_bf16 v[64:67], v[84:87], v[76:79], v[80:83]
	ds_read_b64 v[80:81], v117 offset:6144
	ds_read_b64 v[82:83], v137 offset:6144
	ds_read_b64 v[84:85], v138 offset:6144
	ds_read_b64 v[86:87], v139 offset:6144
	s_waitcnt lgkmcnt(8)
	v_mfma_f32_16x16x32_bf16 v[56:59], v[92:95], v[88:91], v[56:59]
	v_mfma_f32_16x16x32_bf16 v[92:95], v[92:95], v[68:71], v[52:55]
	v_mfma_f32_16x16x32_bf16 v[52:55], v[96:99], v[72:75], v[56:59]
	v_mfma_f32_16x16x32_bf16 v[56:59], v[96:99], v[76:79], v[92:95]
	ds_read_b64 v[92:93], v117 offset:8192
	ds_read_b64 v[94:95], v137 offset:8192
	ds_read_b64 v[96:97], v138 offset:8192
	ds_read_b64 v[98:99], v139 offset:8192
	s_waitcnt lgkmcnt(8)
	v_mfma_f32_16x16x32_bf16 v[48:51], v[100:103], v[88:91], v[48:51]
	v_mfma_f32_16x16x32_bf16 v[100:103], v[100:103], v[68:71], v[44:47]
	v_mfma_f32_16x16x32_bf16 v[44:47], v[104:107], v[72:75], v[48:51]
	v_mfma_f32_16x16x32_bf16 v[48:51], v[104:107], v[76:79], v[100:103]
	ds_read_b64 v[100:101], v117 offset:10240
	ds_read_b64 v[102:103], v137 offset:10240
	ds_read_b64 v[104:105], v138 offset:10240
	ds_read_b64 v[106:107], v139 offset:10240
	s_waitcnt lgkmcnt(8)
	v_mfma_f32_16x16x32_bf16 v[40:43], v[80:83], v[88:91], v[40:43]
	v_mfma_f32_16x16x32_bf16 v[80:83], v[80:83], v[68:71], v[36:39]
	v_mfma_f32_16x16x32_bf16 v[36:39], v[84:87], v[72:75], v[40:43]
	v_mfma_f32_16x16x32_bf16 v[40:43], v[84:87], v[76:79], v[80:83]
	ds_read_b64 v[80:81], v117 offset:12288
	ds_read_b64 v[82:83], v137 offset:12288
	ds_read_b64 v[84:85], v138 offset:12288
	ds_read_b64 v[86:87], v139 offset:12288
	s_waitcnt lgkmcnt(8)
	v_mfma_f32_16x16x32_bf16 v[32:35], v[92:95], v[88:91], v[32:35]
	v_mfma_f32_16x16x32_bf16 v[92:95], v[92:95], v[68:71], v[28:31]
	v_mfma_f32_16x16x32_bf16 v[28:31], v[96:99], v[72:75], v[32:35]
	v_mfma_f32_16x16x32_bf16 v[32:35], v[96:99], v[76:79], v[92:95]
	ds_read_b64 v[92:93], v117 offset:14336
	ds_read_b64 v[94:95], v137 offset:14336
	ds_read_b64 v[96:97], v138 offset:14336
	ds_read_b64 v[98:99], v139 offset:14336
	s_waitcnt lgkmcnt(8)
	v_mfma_f32_16x16x32_bf16 v[24:27], v[100:103], v[88:91], v[24:27]
	v_mfma_f32_16x16x32_bf16 v[100:103], v[100:103], v[68:71], v[16:19]
	v_mfma_f32_16x16x32_bf16 v[16:19], v[104:107], v[72:75], v[24:27]
	v_mfma_f32_16x16x32_bf16 v[100:103], v[104:107], v[76:79], v[100:103]
	s_waitcnt lgkmcnt(4)
	v_mfma_f32_16x16x32_bf16 v[20:23], v[80:83], v[88:91], v[20:23]
	v_mfma_f32_16x16x32_bf16 v[24:27], v[80:83], v[68:71], v[8:11]
	v_mfma_f32_16x16x32_bf16 v[8:11], v[84:87], v[72:75], v[20:23]
	v_mfma_f32_16x16x32_bf16 v[80:83], v[84:87], v[76:79], v[24:27]
	s_waitcnt lgkmcnt(0)
	v_mfma_f32_16x16x32_bf16 v[12:15], v[92:95], v[88:91], v[12:15]
	v_mfma_f32_16x16x32_bf16 v[4:7], v[92:95], v[68:71], v[4:7]
	v_mfma_f32_16x16x32_bf16 v[68:71], v[96:99], v[72:75], v[12:15]
	v_mfma_f32_16x16x32_bf16 v[72:75], v[96:99], v[76:79], v[4:7]
	ds_bpermute_b32 v0, v136, v108
	s_waitcnt lgkmcnt(0)
	v_add_f32_e32 v0, v108, v0
	ds_bpermute_b32 v3, v135, v0
	s_waitcnt lgkmcnt(0)
	v_add_f32_e32 v0, v0, v3
	ds_bpermute_b32 v3, v136, v109
	v_div_scale_f32 v4, s[6:7], v0, v0, 1.0
	v_rcp_f32_e32 v5, v4
	s_waitcnt lgkmcnt(0)
	v_add_f32_e32 v3, v109, v3
	ds_bpermute_b32 v117, v135, v3
	v_fma_f32 v6, -v4, v5, 1.0
	v_fmac_f32_e32 v5, v6, v5
	v_div_scale_f32 v6, vcc, 1.0, v0, 1.0
	v_mul_f32_e32 v7, v6, v5
	v_fma_f32 v12, -v4, v7, v6
	v_fmac_f32_e32 v7, v12, v5
	v_fma_f32 v4, -v4, v7, v6
	s_waitcnt lgkmcnt(0)
	v_pk_add_f32 v[2:3], v[116:117], v[2:3]
	v_div_fmas_f32 v4, v4, v5, v7
	v_div_fixup_f32 v0, v4, v0, 1.0
	v_div_scale_f32 v4, s[6:7], v3, v3, v2
	v_rcp_f32_e32 v5, v4
	v_readlane_b32 s6, v217, 30
	v_readlane_b32 s7, v217, 31
	v_fma_f32 v6, -v4, v5, 1.0
	v_fmac_f32_e32 v5, v6, v5
	v_div_scale_f32 v6, vcc, v2, v3, v2
	v_mul_f32_e32 v7, v6, v5
	v_fma_f32 v12, -v4, v7, v6
	v_fmac_f32_e32 v7, v12, v5
	v_fma_f32 v4, -v4, v7, v6
	v_div_fmas_f32 v4, v4, v5, v7
	v_div_fixup_f32 v2, v4, v3, v2
	v_pk_mul_f32 v[4:5], v[64:65], v[2:3] op_sel_hi:[1,0]
	v_pk_mul_f32 v[6:7], v[66:67], v[2:3] op_sel_hi:[1,0]
	v_pk_fma_f32 v[12:13], v[60:61], v[0:1], v[4:5] op_sel_hi:[1,0,1] neg_lo:[0,0,1] neg_hi:[0,0,1]
	v_pk_fma_f32 v[6:7], v[62:63], v[0:1], v[6:7] op_sel_hi:[1,0,1] neg_lo:[0,0,1] neg_hi:[0,0,1]
	v_mul_f32_e32 v3, v13, v13
	v_fmac_f32_e32 v3, v12, v12
	v_fmac_f32_e32 v3, v6, v6
	v_fmac_f32_e32 v3, v7, v7
	v_pk_mul_f32 v[4:5], v[56:57], v[2:3] op_sel_hi:[1,0]
	v_pk_mul_f32 v[14:15], v[58:59], v[2:3] op_sel_hi:[1,0]
	v_pk_fma_f32 v[22:23], v[52:53], v[0:1], v[4:5] op_sel_hi:[1,0,1] neg_lo:[0,0,1] neg_hi:[0,0,1]
	v_pk_fma_f32 v[14:15], v[54:55], v[0:1], v[14:15] op_sel_hi:[1,0,1] neg_lo:[0,0,1] neg_hi:[0,0,1]
	v_mul_f32_e32 v4, v23, v23
	v_fmac_f32_e32 v4, v22, v22
	v_fmac_f32_e32 v4, v14, v14
	v_fmac_f32_e32 v4, v15, v15
	v_add_f32_e32 v3, v3, v4
	v_pk_mul_f32 v[4:5], v[48:49], v[2:3] op_sel_hi:[1,0]
	v_pk_mul_f32 v[20:21], v[50:51], v[2:3] op_sel_hi:[1,0]
	v_pk_fma_f32 v[44:45], v[44:45], v[0:1], v[4:5] op_sel_hi:[1,0,1] neg_lo:[0,0,1] neg_hi:[0,0,1]
	v_pk_mul_f32 v[4:5], v[40:41], v[2:3] op_sel_hi:[1,0]
	v_pk_fma_f32 v[26:27], v[46:47], v[0:1], v[20:21] op_sel_hi:[1,0,1] neg_lo:[0,0,1] neg_hi:[0,0,1]
	v_pk_fma_f32 v[24:25], v[36:37], v[0:1], v[4:5] op_sel_hi:[1,0,1] neg_lo:[0,0,1] neg_hi:[0,0,1]
	v_pk_mul_f32 v[20:21], v[42:43], v[2:3] op_sel_hi:[1,0]
	v_mov_b32_e32 v36, v25
	v_mov_b32_e32 v37, v45
	v_pk_fma_f32 v[20:21], v[38:39], v[0:1], v[20:21] op_sel_hi:[1,0,1] neg_lo:[0,0,1] neg_hi:[0,0,1]
	v_mov_b32_e32 v4, v24
	v_mov_b32_e32 v5, v44
	v_pk_mul_f32 v[36:37], v[36:37], v[36:37]
	s_nop 0
	v_pk_fma_f32 v[4:5], v[4:5], v[4:5], v[36:37]
	v_mov_b32_e32 v36, v20
	v_mov_b32_e32 v37, v26
	v_pk_fma_f32 v[4:5], v[36:37], v[36:37], v[4:5]
	v_mov_b32_e32 v36, v21
	v_mov_b32_e32 v37, v27
	v_pk_fma_f32 v[4:5], v[36:37], v[36:37], v[4:5]
	v_lshlrev_b32_e32 v37, 4, v134
	v_add_f32_e32 v3, v5, v3
	v_add_f32_e32 v3, v4, v3
	v_pk_mul_f32 v[4:5], v[32:33], v[2:3] op_sel_hi:[1,0]
	v_pk_mul_f32 v[32:33], v[34:35], v[2:3] op_sel_hi:[1,0]
	v_pk_fma_f32 v[34:35], v[28:29], v[0:1], v[4:5] op_sel_hi:[1,0,1] neg_lo:[0,0,1] neg_hi:[0,0,1]
	v_pk_mul_f32 v[4:5], v[100:101], v[2:3] op_sel_hi:[1,0]
	v_pk_mul_f32 v[28:29], v[102:103], v[2:3] op_sel_hi:[1,0]
	v_pk_fma_f32 v[16:17], v[16:17], v[0:1], v[4:5] op_sel_hi:[1,0,1] neg_lo:[0,0,1] neg_hi:[0,0,1]
	v_pk_fma_f32 v[18:19], v[18:19], v[0:1], v[28:29] op_sel_hi:[1,0,1] neg_lo:[0,0,1] neg_hi:[0,0,1]
	v_mov_b32_e32 v28, v17
	v_mov_b32_e32 v29, v35
	v_pk_fma_f32 v[30:31], v[30:31], v[0:1], v[32:33] op_sel_hi:[1,0,1] neg_lo:[0,0,1] neg_hi:[0,0,1]
	v_mov_b32_e32 v4, v16
	v_mov_b32_e32 v5, v34
	v_pk_mul_f32 v[28:29], v[28:29], v[28:29]
	s_nop 0
	v_pk_fma_f32 v[4:5], v[4:5], v[4:5], v[28:29]
	v_mov_b32_e32 v28, v18
	v_mov_b32_e32 v29, v30
	v_pk_fma_f32 v[4:5], v[28:29], v[28:29], v[4:5]
	v_mov_b32_e32 v28, v19
	v_mov_b32_e32 v29, v31
	v_pk_fma_f32 v[4:5], v[28:29], v[28:29], v[4:5]
	s_nop 0
	v_add_f32_e32 v3, v5, v3
	v_add_f32_e32 v36, v4, v3
	v_pk_mul_f32 v[4:5], v[80:81], v[2:3] op_sel_hi:[1,0]
	v_pk_mul_f32 v[28:29], v[82:83], v[2:3] op_sel_hi:[1,0]
	v_pk_fma_f32 v[32:33], v[8:9], v[0:1], v[4:5] op_sel_hi:[1,0,1] neg_lo:[0,0,1] neg_hi:[0,0,1]
	v_pk_mul_f32 v[4:5], v[72:73], v[2:3] op_sel_hi:[1,0]
	v_pk_fma_f32 v[28:29], v[10:11], v[0:1], v[28:29] op_sel_hi:[1,0,1] neg_lo:[0,0,1] neg_hi:[0,0,1]
	v_pk_fma_f32 v[10:11], v[68:69], v[0:1], v[4:5] op_sel_hi:[1,0,1] neg_lo:[0,0,1] neg_hi:[0,0,1]
	v_pk_mul_f32 v[2:3], v[74:75], v[2:3] op_sel_hi:[1,0]
	v_mov_b32_e32 v4, v11
	v_mov_b32_e32 v5, v33
	v_pk_fma_f32 v[8:9], v[70:71], v[0:1], v[2:3] op_sel_hi:[1,0,1] neg_lo:[0,0,1] neg_hi:[0,0,1]
	v_mov_b32_e32 v2, v10
	v_mov_b32_e32 v3, v32
	v_pk_mul_f32 v[4:5], v[4:5], v[4:5]
	s_nop 0
	v_pk_fma_f32 v[2:3], v[2:3], v[2:3], v[4:5]
	v_mov_b32_e32 v4, v8
	v_mov_b32_e32 v5, v28
	v_pk_fma_f32 v[2:3], v[4:5], v[4:5], v[2:3]
	v_mov_b32_e32 v4, v9
	v_mov_b32_e32 v5, v29
	v_pk_fma_f32 v[2:3], v[4:5], v[4:5], v[2:3]
	s_nop 0
	v_add_f32_e32 v0, v3, v36
	v_add_f32_e32 v0, v2, v0
	ds_bpermute_b32 v2, v136, v0
	s_waitcnt lgkmcnt(0)
	v_add_f32_e32 v0, v0, v2
	ds_bpermute_b32 v2, v135, v0
	s_waitcnt lgkmcnt(0)
	v_add_f32_e32 v0, v0, v2
	v_fmamk_f32 v0, v0, 0x3c000000, v144
	v_rsq_f32_e32 v0, v0
	v_lshl_add_u64 v[2:3], v[120:121], 1, s[6:7]
	v_mul_f32_e32 v36, v119, v0
	v_lshlrev_b32_e32 v0, 1, v118
	v_lshl_add_u64 v[2:3], v[2:3], 0, v[0:1]
	v_lshlrev_b32_e32 v0, 3, v134
	v_lshl_add_u64 v[38:39], v[2:3], 0, v[0:1]
	global_load_dwordx4 v[218:221], v37, s[92:93]
	global_load_dwordx4 v[222:225], v37, s[92:93] offset:64
	global_load_dwordx4 v[226:229], v37, s[92:93] offset:128
	global_load_dwordx4 v[230:233], v37, s[92:93] offset:192
	global_load_dwordx4 v[234:237], v37, s[92:93] offset:256
	global_load_dwordx4 v[238:241], v37, s[92:93] offset:320
	global_load_dwordx4 v[242:245], v37, s[92:93] offset:384
	global_load_dwordx4 v[246:249], v37, s[92:93] offset:448
	v_pk_mul_f32 v[12:13], v[12:13], v[36:37] op_sel_hi:[1,0]
	v_pk_mul_f32 v[6:7], v[6:7], v[36:37] op_sel_hi:[1,0]
	v_pk_mul_f32 v[8:9], v[8:9], v[36:37] op_sel_hi:[1,0]
	s_waitcnt vmcnt(0)
	v_pk_mul_f32 v[4:5], v[220:221], v[6:7]
	v_pk_mul_f32 v[2:3], v[218:219], v[12:13]
	v_pk_mul_f32 v[6:7], v[22:23], v[36:37] op_sel_hi:[1,0]
	v_cvt_pk_bf16_f32 v2, v2, v3
	v_cvt_pk_bf16_f32 v3, v4, v5
	global_store_dwordx2 v[38:39], v[2:3], off
	v_pk_mul_f32 v[12:13], v[14:15], v[36:37] op_sel_hi:[1,0]
	v_pk_mul_f32 v[2:3], v[222:223], v[6:7]
	v_pk_mul_f32 v[4:5], v[224:225], v[12:13]
	v_cvt_pk_bf16_f32 v2, v2, v3
	v_cvt_pk_bf16_f32 v3, v4, v5
	global_store_dwordx2 v[38:39], v[2:3], off offset:32
	v_pk_mul_f32 v[6:7], v[44:45], v[36:37] op_sel_hi:[1,0]
	v_pk_mul_f32 v[12:13], v[26:27], v[36:37] op_sel_hi:[1,0]
	v_pk_mul_f32 v[2:3], v[226:227], v[6:7]
	v_pk_mul_f32 v[4:5], v[228:229], v[12:13]
	v_cvt_pk_bf16_f32 v2, v2, v3
	v_cvt_pk_bf16_f32 v3, v4, v5
	global_store_dwordx2 v[38:39], v[2:3], off offset:64
	v_pk_mul_f32 v[6:7], v[24:25], v[36:37] op_sel_hi:[1,0]
	v_pk_mul_f32 v[12:13], v[20:21], v[36:37] op_sel_hi:[1,0]
	v_pk_mul_f32 v[2:3], v[230:231], v[6:7]
	v_pk_mul_f32 v[4:5], v[232:233], v[12:13]
	v_cvt_pk_bf16_f32 v2, v2, v3
	v_cvt_pk_bf16_f32 v3, v4, v5
	global_store_dwordx2 v[38:39], v[2:3], off offset:96
	v_pk_mul_f32 v[6:7], v[34:35], v[36:37] op_sel_hi:[1,0]
	v_pk_mul_f32 v[12:13], v[30:31], v[36:37] op_sel_hi:[1,0]
	v_pk_mul_f32 v[2:3], v[234:235], v[6:7]
	v_pk_mul_f32 v[4:5], v[236:237], v[12:13]
	v_cvt_pk_bf16_f32 v2, v2, v3
	v_cvt_pk_bf16_f32 v3, v4, v5
	global_store_dwordx2 v[38:39], v[2:3], off offset:128
	v_pk_mul_f32 v[6:7], v[16:17], v[36:37] op_sel_hi:[1,0]
	v_pk_mul_f32 v[12:13], v[18:19], v[36:37] op_sel_hi:[1,0]
	v_pk_mul_f32 v[2:3], v[238:239], v[6:7]
	v_pk_mul_f32 v[4:5], v[240:241], v[12:13]
	v_cvt_pk_bf16_f32 v2, v2, v3
	v_cvt_pk_bf16_f32 v3, v4, v5
	global_store_dwordx2 v[38:39], v[2:3], off offset:160
	v_pk_mul_f32 v[6:7], v[32:33], v[36:37] op_sel_hi:[1,0]
	v_pk_mul_f32 v[12:13], v[28:29], v[36:37] op_sel_hi:[1,0]
	v_pk_mul_f32 v[2:3], v[242:243], v[6:7]
	v_pk_mul_f32 v[4:5], v[244:245], v[12:13]
	v_cvt_pk_bf16_f32 v2, v2, v3
	v_cvt_pk_bf16_f32 v3, v4, v5
	global_store_dwordx2 v[38:39], v[2:3], off offset:192
	v_pk_mul_f32 v[6:7], v[10:11], v[36:37] op_sel_hi:[1,0]
	v_pk_mul_f32 v[4:5], v[248:249], v[8:9]
	v_pk_mul_f32 v[2:3], v[246:247], v[6:7]
	s_nop 0
	v_cvt_pk_bf16_f32 v2, v2, v3
	v_cvt_pk_bf16_f32 v3, v4, v5
	global_store_dwordx2 v[38:39], v[2:3], off offset:224
